# EpiResid f32 residual stores without the nt hint (cacheable) on top of v050
# speedup vs baseline: 1.0006x; 1.0006x over previous
.LBB0_490:
	v_lshl_add_u32 v202, s45, 8, v175
	v_lshl_or_b32 v196, s20, 8, v224
	v_ashrrev_i32_e32 v203, 31, v202
	v_ashrrev_i32_e32 v197, 31, v196
	v_lshlrev_b64 v[132:133], 12, v[202:203]
	v_lshl_add_u64 v[198:199], s[16:17], 0, v[132:133]
	v_lshlrev_b64 v[132:133], 2, v[196:197]
	v_or_b32_e32 v204, 16, v202
	v_lshl_add_u64 v[134:135], v[198:199], 0, v[132:133]
	v_ashrrev_i32_e32 v205, 31, v204
	global_load_dwordx4 v[230:233], v[134:135], off offset:16
	global_load_dwordx4 v[234:237], v[134:135], off
	global_load_dwordx4 v[164:167], v[134:135], off offset:528
	global_load_dwordx4 v[168:171], v[134:135], off offset:512
	v_lshlrev_b64 v[134:135], 12, v[204:205]
	v_lshl_add_u64 v[134:135], s[16:17], 0, v[134:135]
	v_or_b32_e32 v200, 32, v202
	v_lshl_add_u64 v[134:135], v[134:135], 0, v[132:133]
	v_ashrrev_i32_e32 v201, 31, v200
	global_load_dwordx4 v[156:159], v[134:135], off offset:16
	global_load_dwordx4 v[160:163], v[134:135], off
	global_load_dwordx4 v[148:151], v[134:135], off offset:528
	global_load_dwordx4 v[152:155], v[134:135], off offset:512
	v_lshlrev_b64 v[134:135], 12, v[200:201]
	v_lshl_add_u64 v[134:135], s[16:17], 0, v[134:135]
	v_lshl_add_u64 v[136:137], v[134:135], 0, v[132:133]
	global_load_dwordx4 v[140:143], v[136:137], off offset:16
	global_load_dwordx4 v[144:147], v[136:137], off
	global_load_dwordx4 v[132:135], v[136:137], off offset:528
	s_nop 0
	global_load_dwordx4 v[136:139], v[136:137], off offset:512
	v_lshlrev_b64 v[206:207], 10, v[202:203]
	v_lshl_add_u64 v[206:207], v[206:207], 0, v[196:197]
	v_mov_b32_e32 v189, v188
	v_cndmask_b32_e64 v216, 0, 1, s[18:19]
	v_lshl_add_u64 v[208:209], v[206:207], 2, s[22:23]
	v_cmp_ne_u32_e64 s[8:9], 1, v216
	s_andn2_b64 vcc, exec, s[18:19]
	s_waitcnt vmcnt(0)
	v_pk_fma_f32 v[126:127], v[188:189], v[126:127], v[232:233]
	v_pk_fma_f32 v[130:131], v[188:189], v[130:131], v[236:237]
	v_pk_fma_f32 v[128:129], v[190:191], v[128:129], v[234:235]
	v_pk_fma_f32 v[124:125], v[190:191], v[124:125], v[230:231]
	global_store_dwordx4 v[208:209], v[128:131], off
	global_store_dwordx4 v[208:209], v[124:127], off offset:16
	s_cbranch_vccnz .LBB0_492
	v_cvt_pk_bf16_f32 v230, v128, v129
	v_cvt_pk_bf16_f32 v231, v130, v131
	v_cvt_pk_bf16_f32 v232, v124, v125
	v_cvt_pk_bf16_f32 v233, v126, v127
	v_lshl_add_u64 v[216:217], v[206:207], 1, s[84:85]
	global_store_dwordx4 v[216:217], v[230:233], off
.LBB0_492:
	v_pk_fma_f32 v[122:123], v[188:189], v[122:123], v[170:171]
	v_pk_fma_f32 v[120:121], v[190:191], v[120:121], v[168:169]
	v_pk_fma_f32 v[118:119], v[188:189], v[118:119], v[166:167]
	v_pk_fma_f32 v[116:117], v[190:191], v[116:117], v[164:165]
	s_and_b64 vcc, exec, s[8:9]
	global_store_dwordx4 v[208:209], v[120:123], off offset:512
	global_store_dwordx4 v[208:209], v[116:119], off offset:528
	s_cbranch_vccnz .LBB0_494
	v_lshlrev_b64 v[168:169], 1, v[206:207]
	v_or_b32_e32 v168, 0x100, v168
	v_cvt_pk_bf16_f32 v164, v120, v121
	v_cvt_pk_bf16_f32 v165, v122, v123
	v_cvt_pk_bf16_f32 v166, v116, v117
	v_cvt_pk_bf16_f32 v167, v118, v119
	v_lshl_add_u64 v[168:169], s[84:85], 0, v[168:169]
	global_store_dwordx4 v[168:169], v[164:167], off

.LBB0_496:
	s_or_b64 exec, exec, s[24:25]
	v_or_b32_e32 v164, 48, v202
	v_ashrrev_i32_e32 v165, 31, v164
	s_waitcnt lgkmcnt(0)
	v_lshlrev_b64 v[116:117], 12, v[164:165]
	v_lshl_add_u64 v[116:117], s[16:17], 0, v[116:117]
	v_lshl_add_u64 v[120:121], v[196:197], 2, v[116:117]
	global_load_dwordx4 v[124:127], v[120:121], off offset:16
	global_load_dwordx4 v[128:131], v[120:121], off
	global_load_dwordx4 v[116:119], v[120:121], off offset:528
	s_nop 0
	global_load_dwordx4 v[120:123], v[120:121], off offset:512
	v_lshlrev_b64 v[166:167], 10, v[204:205]
	v_lshl_add_u64 v[166:167], v[166:167], 0, v[196:197]
	v_mov_b32_e32 v189, v188
	v_pk_fma_f32 v[114:115], v[188:189], v[114:115], v[162:163]
	v_pk_fma_f32 v[112:113], v[190:191], v[112:113], v[160:161]
	v_pk_fma_f32 v[110:111], v[188:189], v[110:111], v[158:159]
	v_pk_fma_f32 v[108:109], v[190:191], v[108:109], v[156:157]
	v_lshl_add_u64 v[156:157], v[166:167], 2, s[22:23]
	s_and_b64 vcc, exec, s[8:9]
	global_store_dwordx4 v[156:157], v[112:115], off
	global_store_dwordx4 v[156:157], v[108:111], off offset:16
	s_cbranch_vccnz .LBB0_498
	v_cvt_pk_bf16_f32 v158, v112, v113
	v_cvt_pk_bf16_f32 v159, v114, v115
	v_cvt_pk_bf16_f32 v160, v108, v109
	v_cvt_pk_bf16_f32 v161, v110, v111
	v_lshl_add_u64 v[162:163], v[166:167], 1, s[84:85]
	global_store_dwordx4 v[162:163], v[158:161], off
.LBB0_498:
	v_pk_fma_f32 v[106:107], v[188:189], v[106:107], v[154:155]
	v_pk_fma_f32 v[104:105], v[190:191], v[104:105], v[152:153]
	v_pk_fma_f32 v[102:103], v[188:189], v[102:103], v[150:151]
	v_pk_fma_f32 v[100:101], v[190:191], v[100:101], v[148:149]
	s_and_b64 vcc, exec, s[8:9]
	global_store_dwordx4 v[156:157], v[104:107], off offset:512
	global_store_dwordx4 v[156:157], v[100:103], off offset:528
	s_cbranch_vccnz .LBB0_500
	v_lshlrev_b64 v[152:153], 1, v[166:167]
	v_or_b32_e32 v152, 0x100, v152
	v_cvt_pk_bf16_f32 v148, v104, v105
	v_cvt_pk_bf16_f32 v149, v106, v107
	v_cvt_pk_bf16_f32 v150, v100, v101
	v_cvt_pk_bf16_f32 v151, v102, v103
	v_lshl_add_u64 v[152:153], s[84:85], 0, v[152:153]
	global_store_dwordx4 v[152:153], v[148:151], off

.LBB0_502:
	s_or_b64 exec, exec, s[24:25]
	v_add_u32_e32 v148, 0x80, v202
	v_ashrrev_i32_e32 v149, 31, v148
	s_waitcnt lgkmcnt(0)
	v_lshlrev_b64 v[100:101], 12, v[148:149]
	v_lshl_add_u64 v[100:101], s[16:17], 0, v[100:101]
	v_lshl_add_u64 v[104:105], v[196:197], 2, v[100:101]
	global_load_dwordx4 v[108:111], v[104:105], off offset:16
	global_load_dwordx4 v[112:115], v[104:105], off
	global_load_dwordx4 v[100:103], v[104:105], off offset:528
	s_nop 0
	global_load_dwordx4 v[104:107], v[104:105], off offset:512
	v_lshlrev_b64 v[150:151], 10, v[200:201]
	v_lshl_add_u64 v[150:151], v[150:151], 0, v[196:197]
	v_mov_b32_e32 v189, v188
	v_pk_fma_f32 v[98:99], v[188:189], v[98:99], v[146:147]
	v_pk_fma_f32 v[96:97], v[190:191], v[96:97], v[144:145]
	v_pk_fma_f32 v[94:95], v[188:189], v[94:95], v[142:143]
	v_pk_fma_f32 v[92:93], v[190:191], v[92:93], v[140:141]
	v_lshl_add_u64 v[140:141], v[150:151], 2, s[22:23]
	s_and_b64 vcc, exec, s[8:9]
	global_store_dwordx4 v[140:141], v[96:99], off
	global_store_dwordx4 v[140:141], v[92:95], off offset:16
	s_cbranch_vccnz .LBB0_504
	v_cvt_pk_bf16_f32 v142, v96, v97
	v_cvt_pk_bf16_f32 v143, v98, v99
	v_cvt_pk_bf16_f32 v144, v92, v93
	v_cvt_pk_bf16_f32 v145, v94, v95
	v_lshl_add_u64 v[146:147], v[150:151], 1, s[84:85]
	global_store_dwordx4 v[146:147], v[142:145], off
.LBB0_504:
	v_pk_fma_f32 v[90:91], v[188:189], v[90:91], v[138:139]
	v_pk_fma_f32 v[88:89], v[190:191], v[88:89], v[136:137]
	v_pk_fma_f32 v[86:87], v[188:189], v[86:87], v[134:135]
	v_pk_fma_f32 v[84:85], v[190:191], v[84:85], v[132:133]
	s_and_b64 vcc, exec, s[8:9]
	global_store_dwordx4 v[140:141], v[88:91], off offset:512
	global_store_dwordx4 v[140:141], v[84:87], off offset:528
	s_cbranch_vccnz .LBB0_506
	v_lshlrev_b64 v[136:137], 1, v[150:151]
	v_or_b32_e32 v136, 0x100, v136
	v_cvt_pk_bf16_f32 v132, v88, v89
	v_cvt_pk_bf16_f32 v133, v90, v91
	v_cvt_pk_bf16_f32 v134, v84, v85
	v_cvt_pk_bf16_f32 v135, v86, v87
	v_lshl_add_u64 v[136:137], s[84:85], 0, v[136:137]
	global_store_dwordx4 v[136:137], v[132:135], off

.LBB0_508:
	s_or_b64 exec, exec, s[24:25]
	s_waitcnt lgkmcnt(0)
	v_lshl_add_u64 v[84:85], v[196:197], 2, v[198:199]
	s_mov_b64 s[24:25], 0x90000
	v_lshl_add_u64 v[88:89], v[84:85], 0, s[24:25]
	v_add_co_u32_e32 v84, vcc, 0x90000, v84
	v_lshlrev_b64 v[132:133], 10, v[164:165]
	s_nop 0
	v_addc_co_u32_e32 v85, vcc, 0, v85, vcc
	global_load_dwordx4 v[96:99], v[84:85], off
	s_nop 0
	global_load_dwordx4 v[84:87], v[88:89], off offset:528
	global_load_dwordx4 v[92:95], v[88:89], off offset:16
	s_nop 0
	global_load_dwordx4 v[88:91], v[88:89], off offset:512
	v_lshl_add_u64 v[132:133], v[132:133], 0, v[196:197]
	v_mov_b32_e32 v189, v188
	s_waitcnt vmcnt(18)
	v_pk_fma_f32 v[82:83], v[188:189], v[82:83], v[130:131]
	v_pk_fma_f32 v[80:81], v[190:191], v[80:81], v[128:129]
	v_pk_fma_f32 v[78:79], v[188:189], v[78:79], v[126:127]
	v_pk_fma_f32 v[76:77], v[190:191], v[76:77], v[124:125]
	v_lshl_add_u64 v[124:125], v[132:133], 2, s[22:23]
	s_and_b64 vcc, exec, s[8:9]
	global_store_dwordx4 v[124:125], v[80:83], off
	global_store_dwordx4 v[124:125], v[76:79], off offset:16
	s_cbranch_vccnz .LBB0_510
	v_cvt_pk_bf16_f32 v126, v80, v81
	v_cvt_pk_bf16_f32 v127, v82, v83
	v_cvt_pk_bf16_f32 v128, v76, v77
	v_cvt_pk_bf16_f32 v129, v78, v79
	v_lshl_add_u64 v[130:131], v[132:133], 1, s[84:85]
	global_store_dwordx4 v[130:131], v[126:129], off
.LBB0_510:
	s_waitcnt vmcnt(18)
	v_pk_fma_f32 v[74:75], v[188:189], v[74:75], v[122:123]
	v_pk_fma_f32 v[72:73], v[190:191], v[72:73], v[120:121]
	v_pk_fma_f32 v[70:71], v[188:189], v[70:71], v[118:119]
	v_pk_fma_f32 v[68:69], v[190:191], v[68:69], v[116:117]
	s_and_b64 vcc, exec, s[8:9]
	global_store_dwordx4 v[124:125], v[72:75], off offset:512
	global_store_dwordx4 v[124:125], v[68:71], off offset:528
	s_cbranch_vccnz .LBB0_512
	v_lshlrev_b64 v[120:121], 1, v[132:133]
	v_or_b32_e32 v120, 0x100, v120
	v_cvt_pk_bf16_f32 v116, v72, v73
	v_cvt_pk_bf16_f32 v117, v74, v75
	v_cvt_pk_bf16_f32 v118, v68, v69
	v_cvt_pk_bf16_f32 v119, v70, v71
	v_lshl_add_u64 v[120:121], s[84:85], 0, v[120:121]
	global_store_dwordx4 v[120:121], v[116:119], off

.LBB0_514:
	s_or_b64 exec, exec, s[24:25]
	v_or_b32_e32 v116, 32, v148
	v_ashrrev_i32_e32 v117, 31, v116
	s_waitcnt lgkmcnt(0)
	v_lshlrev_b64 v[68:69], 12, v[116:117]
	v_lshl_add_u64 v[68:69], s[16:17], 0, v[68:69]
	v_lshl_add_u64 v[72:73], v[196:197], 2, v[68:69]
	global_load_dwordx4 v[76:79], v[72:73], off offset:16
	global_load_dwordx4 v[80:83], v[72:73], off
	global_load_dwordx4 v[68:71], v[72:73], off offset:528
	s_nop 0
	global_load_dwordx4 v[72:75], v[72:73], off offset:512
	v_lshlrev_b64 v[118:119], 10, v[148:149]
	v_lshl_add_u64 v[118:119], v[118:119], 0, v[196:197]
	v_mov_b32_e32 v189, v188
	s_waitcnt vmcnt(18)
	v_pk_fma_f32 v[66:67], v[188:189], v[66:67], v[114:115]
	v_pk_fma_f32 v[64:65], v[190:191], v[64:65], v[112:113]
	v_pk_fma_f32 v[62:63], v[188:189], v[62:63], v[110:111]
	v_pk_fma_f32 v[60:61], v[190:191], v[60:61], v[108:109]
	v_lshl_add_u64 v[108:109], v[118:119], 2, s[22:23]
	s_and_b64 vcc, exec, s[8:9]
	global_store_dwordx4 v[108:109], v[64:67], off
	global_store_dwordx4 v[108:109], v[60:63], off offset:16
	s_cbranch_vccnz .LBB0_516
	v_cvt_pk_bf16_f32 v110, v64, v65
	v_cvt_pk_bf16_f32 v111, v66, v67
	v_cvt_pk_bf16_f32 v112, v60, v61
	v_cvt_pk_bf16_f32 v113, v62, v63
	v_lshl_add_u64 v[114:115], v[118:119], 1, s[84:85]
	global_store_dwordx4 v[114:115], v[110:113], off
.LBB0_516:
	s_waitcnt vmcnt(18)
	v_pk_fma_f32 v[58:59], v[188:189], v[58:59], v[106:107]
	v_pk_fma_f32 v[56:57], v[190:191], v[56:57], v[104:105]
	v_pk_fma_f32 v[54:55], v[188:189], v[54:55], v[102:103]
	v_pk_fma_f32 v[52:53], v[190:191], v[52:53], v[100:101]
	s_and_b64 vcc, exec, s[8:9]
	global_store_dwordx4 v[108:109], v[56:59], off offset:512
	global_store_dwordx4 v[108:109], v[52:55], off offset:528
	s_cbranch_vccnz .LBB0_518
	v_lshlrev_b64 v[104:105], 1, v[118:119]
	v_or_b32_e32 v104, 0x100, v104
	v_cvt_pk_bf16_f32 v100, v56, v57
	v_cvt_pk_bf16_f32 v101, v58, v59
	v_cvt_pk_bf16_f32 v102, v52, v53
	v_cvt_pk_bf16_f32 v103, v54, v55
	v_lshl_add_u64 v[104:105], s[84:85], 0, v[104:105]
	global_store_dwordx4 v[104:105], v[100:103], off

.LBB0_520:
	s_or_b64 exec, exec, s[24:25]
	v_or_b32_e32 v100, 48, v148
	v_ashrrev_i32_e32 v101, 31, v100
	s_waitcnt lgkmcnt(0)
	v_lshlrev_b64 v[52:53], 12, v[100:101]
	v_lshl_add_u64 v[52:53], s[16:17], 0, v[52:53]
	v_lshl_add_u64 v[56:57], v[196:197], 2, v[52:53]
	global_load_dwordx4 v[60:63], v[56:57], off offset:16
	global_load_dwordx4 v[64:67], v[56:57], off
	global_load_dwordx4 v[52:55], v[56:57], off offset:528
	s_nop 0
	global_load_dwordx4 v[56:59], v[56:57], off offset:512
	v_or_b32_e32 v102, 16, v148
	v_ashrrev_i32_e32 v103, 31, v102
	v_lshlrev_b64 v[104:105], 10, v[102:103]
	v_lshl_add_u64 v[104:105], v[104:105], 0, v[196:197]
	v_mov_b32_e32 v189, v188
	s_waitcnt vmcnt(19)
	v_pk_fma_f32 v[50:51], v[188:189], v[50:51], v[98:99]
	v_pk_fma_f32 v[48:49], v[190:191], v[48:49], v[96:97]
	s_waitcnt vmcnt(17)
	v_pk_fma_f32 v[46:47], v[188:189], v[46:47], v[94:95]
	v_pk_fma_f32 v[44:45], v[190:191], v[44:45], v[92:93]
	v_lshl_add_u64 v[92:93], v[104:105], 2, s[22:23]
	s_and_b64 vcc, exec, s[8:9]
	global_store_dwordx4 v[92:93], v[48:51], off
	global_store_dwordx4 v[92:93], v[44:47], off offset:16
	s_cbranch_vccnz .LBB0_522
	v_cvt_pk_bf16_f32 v94, v48, v49
	v_cvt_pk_bf16_f32 v95, v50, v51
	v_cvt_pk_bf16_f32 v96, v44, v45
	v_cvt_pk_bf16_f32 v97, v46, v47
	v_lshl_add_u64 v[98:99], v[104:105], 1, s[84:85]
	global_store_dwordx4 v[98:99], v[94:97], off
.LBB0_522:
	s_waitcnt vmcnt(18)
	v_pk_fma_f32 v[42:43], v[188:189], v[42:43], v[90:91]
	v_pk_fma_f32 v[40:41], v[190:191], v[40:41], v[88:89]
	v_pk_fma_f32 v[38:39], v[188:189], v[38:39], v[86:87]
	v_pk_fma_f32 v[36:37], v[190:191], v[36:37], v[84:85]
	s_and_b64 vcc, exec, s[8:9]
	global_store_dwordx4 v[92:93], v[40:43], off offset:512
	global_store_dwordx4 v[92:93], v[36:39], off offset:528
	s_cbranch_vccnz .LBB0_524
	v_lshlrev_b64 v[88:89], 1, v[104:105]
	v_or_b32_e32 v88, 0x100, v88
	v_cvt_pk_bf16_f32 v84, v40, v41
	v_cvt_pk_bf16_f32 v85, v42, v43
	v_cvt_pk_bf16_f32 v86, v36, v37
	v_cvt_pk_bf16_f32 v87, v38, v39
	v_lshl_add_u64 v[88:89], s[84:85], 0, v[88:89]
	global_store_dwordx4 v[88:89], v[84:87], off

.LBB0_526:
	s_or_b64 exec, exec, s[24:25]
	s_waitcnt lgkmcnt(0)
	v_lshlrev_b64 v[36:37], 10, v[116:117]
	v_lshl_add_u64 v[36:37], v[36:37], 0, v[196:197]
	v_mov_b32_e32 v189, v188
	s_waitcnt vmcnt(14)
	v_pk_fma_f32 v[34:35], v[188:189], v[34:35], v[82:83]
	v_pk_fma_f32 v[32:33], v[190:191], v[32:33], v[80:81]
	v_pk_fma_f32 v[30:31], v[188:189], v[30:31], v[78:79]
	v_pk_fma_f32 v[28:29], v[190:191], v[28:29], v[76:77]
	v_lshl_add_u64 v[38:39], v[36:37], 2, s[22:23]
	s_and_b64 vcc, exec, s[8:9]
	global_store_dwordx4 v[38:39], v[32:35], off
	global_store_dwordx4 v[38:39], v[28:31], off offset:16
	s_cbranch_vccnz .LBB0_528
	v_cvt_pk_bf16_f32 v40, v32, v33
	v_cvt_pk_bf16_f32 v41, v34, v35
	v_cvt_pk_bf16_f32 v42, v28, v29
	v_cvt_pk_bf16_f32 v43, v30, v31
	v_lshl_add_u64 v[44:45], v[36:37], 1, s[84:85]
	global_store_dwordx4 v[44:45], v[40:43], off
.LBB0_528:
	s_waitcnt vmcnt(14)
	v_pk_fma_f32 v[26:27], v[188:189], v[26:27], v[74:75]
	v_pk_fma_f32 v[24:25], v[190:191], v[24:25], v[72:73]
	v_pk_fma_f32 v[22:23], v[188:189], v[22:23], v[70:71]
	v_pk_fma_f32 v[20:21], v[190:191], v[20:21], v[68:69]
	s_and_b64 vcc, exec, s[8:9]
	global_store_dwordx4 v[38:39], v[24:27], off offset:512
	global_store_dwordx4 v[38:39], v[20:23], off offset:528
	s_cbranch_vccnz .LBB0_530
	v_lshlrev_b64 v[40:41], 1, v[36:37]
	v_or_b32_e32 v40, 0x100, v40
	v_cvt_pk_bf16_f32 v36, v24, v25
	v_cvt_pk_bf16_f32 v37, v26, v27
	v_cvt_pk_bf16_f32 v38, v20, v21
	v_cvt_pk_bf16_f32 v39, v22, v23
	v_lshl_add_u64 v[40:41], s[84:85], 0, v[40:41]
	global_store_dwordx4 v[40:41], v[36:39], off

.LBB0_532:
	s_or_b64 exec, exec, s[24:25]
	s_waitcnt lgkmcnt(0)
	v_lshlrev_b64 v[20:21], 10, v[100:101]
	v_lshl_add_u64 v[20:21], v[20:21], 0, v[196:197]
	v_mov_b32_e32 v189, v188
	s_waitcnt vmcnt(10)
	v_pk_fma_f32 v[18:19], v[188:189], v[18:19], v[66:67]
	v_pk_fma_f32 v[16:17], v[190:191], v[16:17], v[64:65]
	v_pk_fma_f32 v[14:15], v[188:189], v[14:15], v[62:63]
	v_pk_fma_f32 v[12:13], v[190:191], v[12:13], v[60:61]
	v_lshl_add_u64 v[22:23], v[20:21], 2, s[22:23]
	s_and_b64 vcc, exec, s[8:9]
	global_store_dwordx4 v[22:23], v[16:19], off
	global_store_dwordx4 v[22:23], v[12:15], off offset:16
	s_cbranch_vccnz .LBB0_534
	v_cvt_pk_bf16_f32 v24, v16, v17
	v_cvt_pk_bf16_f32 v25, v18, v19
	v_cvt_pk_bf16_f32 v26, v12, v13
	v_cvt_pk_bf16_f32 v27, v14, v15
	v_lshl_add_u64 v[28:29], v[20:21], 1, s[84:85]
	global_store_dwordx4 v[28:29], v[24:27], off
.LBB0_534:
	s_waitcnt vmcnt(10)
	v_pk_fma_f32 v[10:11], v[188:189], v[10:11], v[58:59]
	v_pk_fma_f32 v[8:9], v[190:191], v[8:9], v[56:57]
	v_pk_fma_f32 v[6:7], v[188:189], v[6:7], v[54:55]
	v_pk_fma_f32 v[4:5], v[190:191], v[4:5], v[52:53]
	s_and_b64 vcc, exec, s[8:9]
	global_store_dwordx4 v[22:23], v[8:11], off offset:512
	global_store_dwordx4 v[22:23], v[4:7], off offset:528
	s_cbranch_vccnz .LBB0_536
	v_lshlrev_b64 v[24:25], 1, v[20:21]
	v_or_b32_e32 v24, 0x100, v24
	v_cvt_pk_bf16_f32 v20, v8, v9
	v_cvt_pk_bf16_f32 v21, v10, v11
	v_cvt_pk_bf16_f32 v22, v4, v5
	v_cvt_pk_bf16_f32 v23, v6, v7
	v_lshl_add_u64 v[24:25], s[84:85], 0, v[24:25]
	global_store_dwordx4 v[24:25], v[20:23], off
